# v52 plus M0 and base-increment scalar work hoisted away from the QK-to-PV boundary of each attention step (boundary is now load, s_mov m0, nop, load)
# baseline (speedup 1.0000x reference)
.LBB0_618:
	ds_read_b64_tr_b16 v[52:53], v199 offset:24576
	ds_read_b64_tr_b16 v[54:55], v199 offset:25088
	v_mfma_f32_32x32x16_bf16 v[114:129], v[190:193], v[150:153], v[34:49]
	s_add_i32 m0, s31, s70
	s_add_i32 s6, s76, s71
	v_add_f32_e32 v50, v82, v50
	v_add_f32_e32 v194, v83, v194
	v_add_f32_e32 v195, v84, v195
	v_add_f32_e32 v196, v85, v196
	v_add_f32_e32 v50, v86, v50
	v_add_f32_e32 v194, v87, v194
	v_cvt_pk_bf16_f32 v158, v82, v83
	v_cvt_pk_bf16_f32 v159, v84, v85
	ds_read_b64_tr_b16 v[60:61], v199 offset:28672
	ds_read_b64_tr_b16 v[62:63], v199 offset:29184
	v_mfma_f32_32x32x16_bf16 v[98:113], v[186:189], v[150:153], v[34:49]
	v_add_f32_e32 v195, v88, v195
	v_add_f32_e32 v196, v89, v196
	v_add_f32_e32 v50, v90, v50
	v_add_f32_e32 v194, v91, v194
	v_cvt_pk_bf16_f32 v160, v86, v87
	v_cvt_pk_bf16_f32 v161, v88, v89
	ds_read_b64_tr_b16 v[82:83], v199 offset:25600
	ds_read_b64_tr_b16 v[84:85], v199 offset:26112
	v_mfma_f32_32x32x16_bf16 v[114:129], v[182:185], v[138:141], v[114:129]
	v_add_f32_e32 v195, v92, v195
	v_add_f32_e32 v196, v93, v196
	v_add_f32_e32 v50, v94, v50
	v_add_f32_e32 v194, v95, v194
	v_cvt_pk_bf16_f32 v154, v90, v91
	v_cvt_pk_bf16_f32 v155, v92, v93
	ds_read_b64_tr_b16 v[86:87], v199 offset:29696
	ds_read_b64_tr_b16 v[88:89], v199 offset:30208
	v_mfma_f32_32x32x16_bf16 v[98:113], v[178:181], v[138:141], v[98:113]
	v_add_f32_e32 v195, v96, v195
	v_add_f32_e32 v196, v97, v196
	v_add_f32_e32 v50, v66, v50
	v_add_f32_e32 v194, v67, v194
	v_cvt_pk_bf16_f32 v156, v94, v95
	v_cvt_pk_bf16_f32 v157, v96, v97
	ds_read_b64_tr_b16 v[90:91], v199 offset:26624
	ds_read_b64_tr_b16 v[92:93], v199 offset:27136
	v_mfma_f32_32x32x16_bf16 v[114:129], v[174:177], v[134:137], v[114:129]
	v_add_f32_e32 v195, v68, v195
	v_add_f32_e32 v196, v69, v196
	v_add_f32_e32 v50, v70, v50
	v_add_f32_e32 v194, v71, v194
	v_cvt_pk_bf16_f32 v146, v66, v67
	v_cvt_pk_bf16_f32 v147, v68, v69
	ds_read_b64_tr_b16 v[64:65], v199 offset:30720
	ds_read_b64_tr_b16 v[66:67], v199 offset:31232
	v_mfma_f32_32x32x16_bf16 v[98:113], v[170:173], v[134:137], v[98:113]
	v_add_f32_e32 v195, v72, v195
	v_add_f32_e32 v196, v73, v196
	v_add_f32_e32 v50, v74, v50
	v_add_f32_e32 v194, v75, v194
	v_cvt_pk_bf16_f32 v148, v70, v71
	v_cvt_pk_bf16_f32 v149, v72, v73
	ds_read_b64_tr_b16 v[68:69], v199 offset:27648
	ds_read_b64_tr_b16 v[70:71], v199 offset:28160
	v_mfma_f32_32x32x16_bf16 v[114:129], v[166:169], v[130:133], v[114:129]
	v_add_f32_e32 v195, v76, v195
	v_add_f32_e32 v196, v77, v196
	v_add_f32_e32 v50, v78, v50
	v_add_f32_e32 v194, v79, v194
	v_cvt_pk_bf16_f32 v142, v74, v75
	v_cvt_pk_bf16_f32 v143, v76, v77
	ds_read_b64_tr_b16 v[72:73], v199 offset:31744
	ds_read_b64_tr_b16 v[74:75], v199 offset:32256
	v_mfma_f32_32x32x16_bf16 v[98:113], v[162:165], v[130:133], v[98:113]
	v_add_f32_e32 v195, v80, v195
	v_add_f32_e32 v196, v81, v196
	v_cvt_pk_bf16_f32 v144, v78, v79
	v_cvt_pk_bf16_f32 v145, v80, v81
	global_load_lds_dwordx4 v197, s[98:99]
	s_mov_b32 m0, s6
	s_nop 0
	global_load_lds_dwordx4 v205, s[98:99]
	s_waitcnt lgkmcnt(14)
	v_mfma_f32_32x32x16_bf16 v[2:17], v[158:161], v[52:55], v[2:17]
	v_exp_f32_e32 v114, v114
	v_exp_f32_e32 v115, v115
	v_exp_f32_e32 v116, v116
	v_exp_f32_e32 v117, v117
	s_waitcnt lgkmcnt(12)
	v_mfma_f32_32x32x16_bf16 v[18:33], v[158:161], v[60:63], v[18:33]
	v_exp_f32_e32 v118, v118
	v_exp_f32_e32 v119, v119
	v_exp_f32_e32 v120, v120
	v_exp_f32_e32 v121, v121
	ds_read_b128 v[60:63], v204
	ds_read_b128 v[162:165], v204 offset:512
	s_waitcnt lgkmcnt(12)
	v_mfma_f32_32x32x16_bf16 v[2:17], v[154:157], v[82:85], v[2:17]
	v_exp_f32_e32 v122, v122
	v_exp_f32_e32 v123, v123
	v_exp_f32_e32 v124, v124
	v_exp_f32_e32 v125, v125
	ds_read_b128 v[166:169], v204 offset:2048
	ds_read_b128 v[170:173], v204 offset:2560
	s_waitcnt lgkmcnt(12)
	v_mfma_f32_32x32x16_bf16 v[18:33], v[154:157], v[86:89], v[18:33]
	v_exp_f32_e32 v126, v126
	v_exp_f32_e32 v127, v127
	v_exp_f32_e32 v128, v128
	v_exp_f32_e32 v129, v129
	ds_read_b128 v[174:177], v204 offset:4096
	ds_read_b128 v[178:181], v204 offset:4608
	s_waitcnt lgkmcnt(12)
	v_mfma_f32_32x32x16_bf16 v[2:17], v[146:149], v[90:93], v[2:17]
	v_exp_f32_e32 v98, v98
	v_exp_f32_e32 v99, v99
	v_exp_f32_e32 v100, v100
	v_exp_f32_e32 v101, v101
	ds_read_b128 v[182:185], v204 offset:6144
	ds_read_b128 v[52:55], v204 offset:6656
	s_waitcnt lgkmcnt(12)
	v_mfma_f32_32x32x16_bf16 v[18:33], v[146:149], v[64:67], v[18:33]
	v_exp_f32_e32 v102, v102
	v_exp_f32_e32 v103, v103
	v_exp_f32_e32 v104, v104
	v_exp_f32_e32 v105, v105
	s_waitcnt lgkmcnt(10)
	v_mfma_f32_32x32x16_bf16 v[2:17], v[142:145], v[68:71], v[2:17]
	v_exp_f32_e32 v106, v106
	v_exp_f32_e32 v107, v107
	v_exp_f32_e32 v108, v108
	v_exp_f32_e32 v109, v109
	s_waitcnt lgkmcnt(8)
	v_mfma_f32_32x32x16_bf16 v[18:33], v[142:145], v[72:75], v[18:33]
	v_exp_f32_e32 v110, v110
	v_exp_f32_e32 v111, v111
	v_exp_f32_e32 v112, v112
	v_exp_f32_e32 v113, v113
	s_add_u32 s98, s98, 0x2000
	s_addc_u32 s99, s99, 0
	s_add_i32 s6, s76, 0x2000
	s_cmpk_lg_i32 s76, 0x4000
	s_cselect_b32 s31, s6, 0
	s_waitcnt vmcnt(2) lgkmcnt(0)
	s_barrier
; #define WAIT_BAR(N) asm volatile("s_waitcnt vmcnt(" #N ") lgkmcnt(0)\n\ts_barrier":::"memory")
;   #define RESC() do{ if(resc){ asm volatile("s_waitcnt lgkmcnt(0)":::"memory"); \
;       _Pragma("unroll") for(int d_=0;d_<2;++d_) _Pragma("unroll") for(int r=0;r<16;++r)o[d_][r]*=wsf[crow(r,hi)]; } }while(0)
;   #define ROT() do{sl_prev=sl_cur;sl_cur=sl_next;sl_next=(sl_next==(NSLOT-1)*SLOTB)?0:sl_next+SLOTB;}while(0)
; template<int THRL> __device__ __forceinline__ void attn_unit(const bf16*Qu,const bf16*__restrict__ Kh,const bf16*__restrict__ Vh,bf16*Ou,const int NT,const float shift,char*shm){
;     ...
;     STEP(pB0,pB1,pA0,pA1,t,true,true,true);     WAIT_BAR(2); RESC(); ROT();
;     STEP(pA0,pA1,pB0,pB1,t+1,true,true,true);   WAIT_BAR(2); RESC(); ROT();
	ds_read_b64_tr_b16 v[186:187], v200 offset:24576
	ds_read_b64_tr_b16 v[188:189], v200 offset:25088
	v_mfma_f32_32x32x16_bf16 v[82:97], v[60:63], v[150:153], v[34:49]
	s_add_i32 m0, s76, s70
	s_add_i32 s6, s31, s71
	v_add_f32_e32 v50, v114, v50
	v_add_f32_e32 v194, v115, v194
	v_add_f32_e32 v195, v116, v195
	v_add_f32_e32 v196, v117, v196
	v_add_f32_e32 v50, v118, v50
	v_add_f32_e32 v194, v119, v194
	v_cvt_pk_bf16_f32 v158, v114, v115
	v_cvt_pk_bf16_f32 v159, v116, v117
	ds_read_b64_tr_b16 v[60:61], v200 offset:28672
	ds_read_b64_tr_b16 v[62:63], v200 offset:29184
	v_mfma_f32_32x32x16_bf16 v[66:81], v[162:165], v[150:153], v[34:49]
	v_add_f32_e32 v195, v120, v195
	v_add_f32_e32 v196, v121, v196
	v_add_f32_e32 v50, v122, v50
	v_add_f32_e32 v194, v123, v194
	v_cvt_pk_bf16_f32 v160, v118, v119
	v_cvt_pk_bf16_f32 v161, v120, v121
	ds_read_b64_tr_b16 v[114:115], v200 offset:25600
	ds_read_b64_tr_b16 v[116:117], v200 offset:26112
	v_mfma_f32_32x32x16_bf16 v[82:97], v[166:169], v[138:141], v[82:97]
	v_add_f32_e32 v195, v124, v195
	v_add_f32_e32 v196, v125, v196
	v_add_f32_e32 v50, v126, v50
	v_add_f32_e32 v194, v127, v194
	v_cvt_pk_bf16_f32 v154, v122, v123
	v_cvt_pk_bf16_f32 v155, v124, v125
	ds_read_b64_tr_b16 v[118:119], v200 offset:29696
	ds_read_b64_tr_b16 v[120:121], v200 offset:30208
	v_mfma_f32_32x32x16_bf16 v[66:81], v[170:173], v[138:141], v[66:81]
	v_add_f32_e32 v195, v128, v195
	v_add_f32_e32 v196, v129, v196
	v_add_f32_e32 v50, v98, v50
	v_add_f32_e32 v194, v99, v194
	v_cvt_pk_bf16_f32 v156, v126, v127
	v_cvt_pk_bf16_f32 v157, v128, v129
	ds_read_b64_tr_b16 v[122:123], v200 offset:26624
	ds_read_b64_tr_b16 v[124:125], v200 offset:27136
	v_mfma_f32_32x32x16_bf16 v[82:97], v[174:177], v[134:137], v[82:97]
	v_add_f32_e32 v195, v100, v195
	v_add_f32_e32 v196, v101, v196
	v_add_f32_e32 v50, v102, v50
	v_add_f32_e32 v194, v103, v194
	v_cvt_pk_bf16_f32 v146, v98, v99
	v_cvt_pk_bf16_f32 v147, v100, v101
	ds_read_b64_tr_b16 v[98:99], v200 offset:30720
	ds_read_b64_tr_b16 v[100:101], v200 offset:31232
	v_mfma_f32_32x32x16_bf16 v[66:81], v[178:181], v[134:137], v[66:81]
	v_add_f32_e32 v195, v104, v195
	v_add_f32_e32 v196, v105, v196
	v_add_f32_e32 v50, v106, v50
	v_add_f32_e32 v194, v107, v194
	v_cvt_pk_bf16_f32 v148, v102, v103
	v_cvt_pk_bf16_f32 v149, v104, v105
	ds_read_b64_tr_b16 v[102:103], v200 offset:27648
	ds_read_b64_tr_b16 v[104:105], v200 offset:28160
	v_mfma_f32_32x32x16_bf16 v[82:97], v[182:185], v[130:133], v[82:97]
	v_add_f32_e32 v195, v108, v195
	v_add_f32_e32 v196, v109, v196
	v_add_f32_e32 v50, v110, v50
	v_add_f32_e32 v194, v111, v194
	v_cvt_pk_bf16_f32 v142, v106, v107
	v_cvt_pk_bf16_f32 v143, v108, v109
	ds_read_b64_tr_b16 v[106:107], v200 offset:31744
	ds_read_b64_tr_b16 v[108:109], v200 offset:32256
	v_mfma_f32_32x32x16_bf16 v[66:81], v[52:55], v[130:133], v[66:81]
	v_add_f32_e32 v195, v112, v195
	v_add_f32_e32 v196, v113, v196
	v_cvt_pk_bf16_f32 v144, v110, v111
	v_cvt_pk_bf16_f32 v145, v112, v113
	global_load_lds_dwordx4 v197, s[98:99]
	s_mov_b32 m0, s6
	s_nop 0
	global_load_lds_dwordx4 v205, s[98:99]
	s_waitcnt lgkmcnt(14)
	v_mfma_f32_32x32x16_bf16 v[2:17], v[158:161], v[186:189], v[2:17]
	v_exp_f32_e32 v82, v82
	v_exp_f32_e32 v83, v83
	v_exp_f32_e32 v84, v84
	v_exp_f32_e32 v85, v85
	s_waitcnt lgkmcnt(12)
	v_mfma_f32_32x32x16_bf16 v[18:33], v[158:161], v[60:63], v[18:33]
	v_exp_f32_e32 v86, v86
	v_exp_f32_e32 v87, v87
	v_exp_f32_e32 v88, v88
	v_exp_f32_e32 v89, v89
	ds_read_b128 v[190:193], v202
	ds_read_b128 v[186:189], v202 offset:512
	s_waitcnt lgkmcnt(12)
	v_mfma_f32_32x32x16_bf16 v[2:17], v[154:157], v[114:117], v[2:17]
	v_exp_f32_e32 v90, v90
	v_exp_f32_e32 v91, v91
	v_exp_f32_e32 v92, v92
	v_exp_f32_e32 v93, v93
	ds_read_b128 v[182:185], v202 offset:2048
	ds_read_b128 v[178:181], v202 offset:2560
	s_waitcnt lgkmcnt(12)
	v_mfma_f32_32x32x16_bf16 v[18:33], v[154:157], v[118:121], v[18:33]
	v_exp_f32_e32 v94, v94
	v_exp_f32_e32 v95, v95
	v_exp_f32_e32 v96, v96
	v_exp_f32_e32 v97, v97
	ds_read_b128 v[174:177], v202 offset:4096
	ds_read_b128 v[170:173], v202 offset:4608
	s_waitcnt lgkmcnt(12)
	v_mfma_f32_32x32x16_bf16 v[2:17], v[146:149], v[122:125], v[2:17]
	v_exp_f32_e32 v66, v66
	v_exp_f32_e32 v67, v67
	v_exp_f32_e32 v68, v68
	v_exp_f32_e32 v69, v69
	ds_read_b128 v[166:169], v202 offset:6144
	ds_read_b128 v[162:165], v202 offset:6656
	s_waitcnt lgkmcnt(12)
	v_mfma_f32_32x32x16_bf16 v[18:33], v[146:149], v[98:101], v[18:33]
	v_exp_f32_e32 v70, v70
	v_exp_f32_e32 v71, v71
	v_exp_f32_e32 v72, v72
	v_exp_f32_e32 v73, v73
	s_waitcnt lgkmcnt(10)
	v_mfma_f32_32x32x16_bf16 v[2:17], v[142:145], v[102:105], v[2:17]
	v_exp_f32_e32 v74, v74
	v_exp_f32_e32 v75, v75
	v_exp_f32_e32 v76, v76
	v_exp_f32_e32 v77, v77
	s_waitcnt lgkmcnt(8)
	v_mfma_f32_32x32x16_bf16 v[18:33], v[142:145], v[106:109], v[18:33]
	v_exp_f32_e32 v78, v78
	v_exp_f32_e32 v79, v79
	v_exp_f32_e32 v80, v80
	v_exp_f32_e32 v81, v81
	s_add_u32 s98, s98, 0x2000
	s_addc_u32 s99, s99, 0
	s_add_i32 s6, s31, 0x2000
	s_cmpk_lg_i32 s31, 0x4000
	s_mov_b32 s24, s76
	s_cselect_b32 s76, s6, 0
	s_add_i32 s26, s26, 2
	s_cmp_gt_i32 s26, s91
	s_cbranch_scc1 .Lattn_exit
	s_waitcnt vmcnt(2) lgkmcnt(0)
	s_barrier
.Lattn_cpB:
	ds_read_b64_tr_b16 v[52:53], v201 offset:24576
	ds_read_b64_tr_b16 v[54:55], v201 offset:25088
	v_mfma_f32_32x32x16_bf16 v[114:129], v[190:193], v[150:153], v[34:49]
	s_add_i32 m0, s31, s70
	s_add_i32 s6, s76, s71
	v_add_f32_e32 v50, v82, v50
	v_add_f32_e32 v194, v83, v194
	v_add_f32_e32 v195, v84, v195
	v_add_f32_e32 v196, v85, v196
	v_add_f32_e32 v50, v86, v50
	v_add_f32_e32 v194, v87, v194
	v_cvt_pk_bf16_f32 v158, v82, v83
	v_cvt_pk_bf16_f32 v159, v84, v85
	ds_read_b64_tr_b16 v[60:61], v201 offset:28672
	ds_read_b64_tr_b16 v[62:63], v201 offset:29184
	v_mfma_f32_32x32x16_bf16 v[98:113], v[186:189], v[150:153], v[34:49]
	v_add_f32_e32 v195, v88, v195
	v_add_f32_e32 v196, v89, v196
	v_add_f32_e32 v50, v90, v50
	v_add_f32_e32 v194, v91, v194
	v_cvt_pk_bf16_f32 v160, v86, v87
	v_cvt_pk_bf16_f32 v161, v88, v89
	ds_read_b64_tr_b16 v[82:83], v201 offset:25600
	ds_read_b64_tr_b16 v[84:85], v201 offset:26112
	v_mfma_f32_32x32x16_bf16 v[114:129], v[182:185], v[138:141], v[114:129]
	v_add_f32_e32 v195, v92, v195
	v_add_f32_e32 v196, v93, v196
	v_add_f32_e32 v50, v94, v50
	v_add_f32_e32 v194, v95, v194
	v_cvt_pk_bf16_f32 v154, v90, v91
	v_cvt_pk_bf16_f32 v155, v92, v93
	ds_read_b64_tr_b16 v[86:87], v201 offset:29696
	ds_read_b64_tr_b16 v[88:89], v201 offset:30208
	v_mfma_f32_32x32x16_bf16 v[98:113], v[178:181], v[138:141], v[98:113]
	v_add_f32_e32 v195, v96, v195
	v_add_f32_e32 v196, v97, v196
	v_add_f32_e32 v50, v66, v50
	v_add_f32_e32 v194, v67, v194
	v_cvt_pk_bf16_f32 v156, v94, v95
	v_cvt_pk_bf16_f32 v157, v96, v97
	ds_read_b64_tr_b16 v[90:91], v201 offset:26624
	ds_read_b64_tr_b16 v[92:93], v201 offset:27136
	v_mfma_f32_32x32x16_bf16 v[114:129], v[174:177], v[134:137], v[114:129]
	v_add_f32_e32 v195, v68, v195
	v_add_f32_e32 v196, v69, v196
	v_add_f32_e32 v50, v70, v50
	v_add_f32_e32 v194, v71, v194
	v_cvt_pk_bf16_f32 v146, v66, v67
	v_cvt_pk_bf16_f32 v147, v68, v69
	ds_read_b64_tr_b16 v[64:65], v201 offset:30720
	ds_read_b64_tr_b16 v[66:67], v201 offset:31232
	v_mfma_f32_32x32x16_bf16 v[98:113], v[170:173], v[134:137], v[98:113]
	v_add_f32_e32 v195, v72, v195
	v_add_f32_e32 v196, v73, v196
	v_add_f32_e32 v50, v74, v50
	v_add_f32_e32 v194, v75, v194
	v_cvt_pk_bf16_f32 v148, v70, v71
	v_cvt_pk_bf16_f32 v149, v72, v73
	ds_read_b64_tr_b16 v[68:69], v201 offset:27648
	ds_read_b64_tr_b16 v[70:71], v201 offset:28160
	v_mfma_f32_32x32x16_bf16 v[114:129], v[166:169], v[130:133], v[114:129]
	v_add_f32_e32 v195, v76, v195
	v_add_f32_e32 v196, v77, v196
	v_add_f32_e32 v50, v78, v50
	v_add_f32_e32 v194, v79, v194
	v_cvt_pk_bf16_f32 v142, v74, v75
	v_cvt_pk_bf16_f32 v143, v76, v77
	ds_read_b64_tr_b16 v[72:73], v201 offset:31744
	ds_read_b64_tr_b16 v[74:75], v201 offset:32256
	v_mfma_f32_32x32x16_bf16 v[98:113], v[162:165], v[130:133], v[98:113]
	v_add_f32_e32 v195, v80, v195
	v_add_f32_e32 v196, v81, v196
	v_cvt_pk_bf16_f32 v144, v78, v79
	v_cvt_pk_bf16_f32 v145, v80, v81
	global_load_lds_dwordx4 v197, s[98:99]
	s_mov_b32 m0, s6
	s_nop 0
	global_load_lds_dwordx4 v205, s[98:99]
	s_waitcnt lgkmcnt(14)
	v_mfma_f32_32x32x16_bf16 v[2:17], v[158:161], v[52:55], v[2:17]
	v_exp_f32_e32 v114, v114
	v_exp_f32_e32 v115, v115
	v_exp_f32_e32 v116, v116
	v_exp_f32_e32 v117, v117
	s_waitcnt lgkmcnt(12)
	v_mfma_f32_32x32x16_bf16 v[18:33], v[158:161], v[60:63], v[18:33]
	v_exp_f32_e32 v118, v118
	v_exp_f32_e32 v119, v119
	v_exp_f32_e32 v120, v120
	v_exp_f32_e32 v121, v121
	ds_read_b128 v[60:63], v203
	ds_read_b128 v[162:165], v203 offset:512
	s_waitcnt lgkmcnt(12)
	v_mfma_f32_32x32x16_bf16 v[2:17], v[154:157], v[82:85], v[2:17]
	v_exp_f32_e32 v122, v122
	v_exp_f32_e32 v123, v123
	v_exp_f32_e32 v124, v124
	v_exp_f32_e32 v125, v125
	ds_read_b128 v[166:169], v203 offset:2048
	ds_read_b128 v[170:173], v203 offset:2560
	s_waitcnt lgkmcnt(12)
	v_mfma_f32_32x32x16_bf16 v[18:33], v[154:157], v[86:89], v[18:33]
	v_exp_f32_e32 v126, v126
	v_exp_f32_e32 v127, v127
	v_exp_f32_e32 v128, v128
	v_exp_f32_e32 v129, v129
	ds_read_b128 v[174:177], v203 offset:4096
	ds_read_b128 v[178:181], v203 offset:4608
	s_waitcnt lgkmcnt(12)
	v_mfma_f32_32x32x16_bf16 v[2:17], v[146:149], v[90:93], v[2:17]
	v_exp_f32_e32 v98, v98
	v_exp_f32_e32 v99, v99
	v_exp_f32_e32 v100, v100
	v_exp_f32_e32 v101, v101
	ds_read_b128 v[182:185], v203 offset:6144
	ds_read_b128 v[52:55], v203 offset:6656
	s_waitcnt lgkmcnt(12)
	v_mfma_f32_32x32x16_bf16 v[18:33], v[146:149], v[64:67], v[18:33]
	v_exp_f32_e32 v102, v102
	v_exp_f32_e32 v103, v103
	v_exp_f32_e32 v104, v104
	v_exp_f32_e32 v105, v105
	s_waitcnt lgkmcnt(10)
	v_mfma_f32_32x32x16_bf16 v[2:17], v[142:145], v[68:71], v[2:17]
	v_exp_f32_e32 v106, v106
	v_exp_f32_e32 v107, v107
	v_exp_f32_e32 v108, v108
	v_exp_f32_e32 v109, v109
	s_waitcnt lgkmcnt(8)
	v_mfma_f32_32x32x16_bf16 v[18:33], v[142:145], v[72:75], v[18:33]
	v_exp_f32_e32 v110, v110
	v_exp_f32_e32 v111, v111
	v_exp_f32_e32 v112, v112
	v_exp_f32_e32 v113, v113
	s_add_u32 s98, s98, 0x2000
	s_addc_u32 s99, s99, 0
	s_add_i32 s6, s76, 0x2000
	s_cmpk_lg_i32 s76, 0x4000
	s_cselect_b32 s31, s6, 0
	s_waitcnt vmcnt(2) lgkmcnt(0)
	s_barrier
; #define WAIT_BAR(N) asm volatile("s_waitcnt vmcnt(" #N ") lgkmcnt(0)\n\ts_barrier":::"memory")
;   #define RESC() do{ if(resc){ asm volatile("s_waitcnt lgkmcnt(0)":::"memory"); \
;       _Pragma("unroll") for(int d_=0;d_<2;++d_) _Pragma("unroll") for(int r=0;r<16;++r)o[d_][r]*=wsf[crow(r,hi)]; } }while(0)
;   #define ROT() do{sl_prev=sl_cur;sl_cur=sl_next;sl_next=(sl_next==(NSLOT-1)*SLOTB)?0:sl_next+SLOTB;}while(0)
; template<int THRL> __device__ __forceinline__ void attn_unit(const bf16*Qu,const bf16*__restrict__ Kh,const bf16*__restrict__ Vh,bf16*Ou,const int NT,const float shift,char*shm){
;     ...
;     STEP(pB0,pB1,pA0,pA1,t,true,true,true);     WAIT_BAR(2); RESC(); ROT();
;     STEP(pA0,pA1,pB0,pB1,t+1,true,true,true);   WAIT_BAR(2); RESC(); ROT();
	ds_read_b64_tr_b16 v[186:187], v199 offset:24576
	ds_read_b64_tr_b16 v[188:189], v199 offset:25088
	v_mfma_f32_32x32x16_bf16 v[82:97], v[60:63], v[150:153], v[34:49]
	s_add_i32 m0, s76, s70
	s_add_i32 s6, s31, s71
	v_add_f32_e32 v50, v114, v50
	v_add_f32_e32 v194, v115, v194
	v_add_f32_e32 v195, v116, v195
	v_add_f32_e32 v196, v117, v196
	v_add_f32_e32 v50, v118, v50
	v_add_f32_e32 v194, v119, v194
	v_cvt_pk_bf16_f32 v158, v114, v115
	v_cvt_pk_bf16_f32 v159, v116, v117
	ds_read_b64_tr_b16 v[60:61], v199 offset:28672
	ds_read_b64_tr_b16 v[62:63], v199 offset:29184
	v_mfma_f32_32x32x16_bf16 v[66:81], v[162:165], v[150:153], v[34:49]
	v_add_f32_e32 v195, v120, v195
	v_add_f32_e32 v196, v121, v196
	v_add_f32_e32 v50, v122, v50
	v_add_f32_e32 v194, v123, v194
	v_cvt_pk_bf16_f32 v160, v118, v119
	v_cvt_pk_bf16_f32 v161, v120, v121
	ds_read_b64_tr_b16 v[114:115], v199 offset:25600
	ds_read_b64_tr_b16 v[116:117], v199 offset:26112
	v_mfma_f32_32x32x16_bf16 v[82:97], v[166:169], v[138:141], v[82:97]
	v_add_f32_e32 v195, v124, v195
	v_add_f32_e32 v196, v125, v196
	v_add_f32_e32 v50, v126, v50
	v_add_f32_e32 v194, v127, v194
	v_cvt_pk_bf16_f32 v154, v122, v123
	v_cvt_pk_bf16_f32 v155, v124, v125
	ds_read_b64_tr_b16 v[118:119], v199 offset:29696
	ds_read_b64_tr_b16 v[120:121], v199 offset:30208
	v_mfma_f32_32x32x16_bf16 v[66:81], v[170:173], v[138:141], v[66:81]
	v_add_f32_e32 v195, v128, v195
	v_add_f32_e32 v196, v129, v196
	v_add_f32_e32 v50, v98, v50
	v_add_f32_e32 v194, v99, v194
	v_cvt_pk_bf16_f32 v156, v126, v127
	v_cvt_pk_bf16_f32 v157, v128, v129
	ds_read_b64_tr_b16 v[122:123], v199 offset:26624
	ds_read_b64_tr_b16 v[124:125], v199 offset:27136
	v_mfma_f32_32x32x16_bf16 v[82:97], v[174:177], v[134:137], v[82:97]
	v_add_f32_e32 v195, v100, v195
	v_add_f32_e32 v196, v101, v196
	v_add_f32_e32 v50, v102, v50
	v_add_f32_e32 v194, v103, v194
	v_cvt_pk_bf16_f32 v146, v98, v99
	v_cvt_pk_bf16_f32 v147, v100, v101
	ds_read_b64_tr_b16 v[98:99], v199 offset:30720
	ds_read_b64_tr_b16 v[100:101], v199 offset:31232
	v_mfma_f32_32x32x16_bf16 v[66:81], v[178:181], v[134:137], v[66:81]
	v_add_f32_e32 v195, v104, v195
	v_add_f32_e32 v196, v105, v196
	v_add_f32_e32 v50, v106, v50
	v_add_f32_e32 v194, v107, v194
	v_cvt_pk_bf16_f32 v148, v102, v103
	v_cvt_pk_bf16_f32 v149, v104, v105
	ds_read_b64_tr_b16 v[102:103], v199 offset:27648
	ds_read_b64_tr_b16 v[104:105], v199 offset:28160
	v_mfma_f32_32x32x16_bf16 v[82:97], v[182:185], v[130:133], v[82:97]
	v_add_f32_e32 v195, v108, v195
	v_add_f32_e32 v196, v109, v196
	v_add_f32_e32 v50, v110, v50
	v_add_f32_e32 v194, v111, v194
	v_cvt_pk_bf16_f32 v142, v106, v107
	v_cvt_pk_bf16_f32 v143, v108, v109
	ds_read_b64_tr_b16 v[106:107], v199 offset:31744
	ds_read_b64_tr_b16 v[108:109], v199 offset:32256
	v_mfma_f32_32x32x16_bf16 v[66:81], v[52:55], v[130:133], v[66:81]
	v_add_f32_e32 v195, v112, v195
	v_add_f32_e32 v196, v113, v196
	v_cvt_pk_bf16_f32 v144, v110, v111
	v_cvt_pk_bf16_f32 v145, v112, v113
	global_load_lds_dwordx4 v197, s[98:99]
	s_mov_b32 m0, s6
	s_nop 0
	global_load_lds_dwordx4 v205, s[98:99]
	s_waitcnt lgkmcnt(14)
	v_mfma_f32_32x32x16_bf16 v[2:17], v[158:161], v[186:189], v[2:17]
	v_exp_f32_e32 v82, v82
	v_exp_f32_e32 v83, v83
	v_exp_f32_e32 v84, v84
	v_exp_f32_e32 v85, v85
	s_waitcnt lgkmcnt(12)
	v_mfma_f32_32x32x16_bf16 v[18:33], v[158:161], v[60:63], v[18:33]
	v_exp_f32_e32 v86, v86
	v_exp_f32_e32 v87, v87
	v_exp_f32_e32 v88, v88
	v_exp_f32_e32 v89, v89
	ds_read_b128 v[190:193], v204
	ds_read_b128 v[186:189], v204 offset:512
	s_waitcnt lgkmcnt(12)
	v_mfma_f32_32x32x16_bf16 v[2:17], v[154:157], v[114:117], v[2:17]
	v_exp_f32_e32 v90, v90
	v_exp_f32_e32 v91, v91
	v_exp_f32_e32 v92, v92
	v_exp_f32_e32 v93, v93
	ds_read_b128 v[182:185], v204 offset:2048
	ds_read_b128 v[178:181], v204 offset:2560
	s_waitcnt lgkmcnt(12)
	v_mfma_f32_32x32x16_bf16 v[18:33], v[154:157], v[118:121], v[18:33]
	v_exp_f32_e32 v94, v94
	v_exp_f32_e32 v95, v95
	v_exp_f32_e32 v96, v96
	v_exp_f32_e32 v97, v97
	ds_read_b128 v[174:177], v204 offset:4096
	ds_read_b128 v[170:173], v204 offset:4608
	s_waitcnt lgkmcnt(12)
	v_mfma_f32_32x32x16_bf16 v[2:17], v[146:149], v[122:125], v[2:17]
	v_exp_f32_e32 v66, v66
	v_exp_f32_e32 v67, v67
	v_exp_f32_e32 v68, v68
	v_exp_f32_e32 v69, v69
	ds_read_b128 v[166:169], v204 offset:6144
	ds_read_b128 v[162:165], v204 offset:6656
	s_waitcnt lgkmcnt(12)
	v_mfma_f32_32x32x16_bf16 v[18:33], v[146:149], v[98:101], v[18:33]
	v_exp_f32_e32 v70, v70
	v_exp_f32_e32 v71, v71
	v_exp_f32_e32 v72, v72
	v_exp_f32_e32 v73, v73
	s_waitcnt lgkmcnt(10)
	v_mfma_f32_32x32x16_bf16 v[2:17], v[142:145], v[102:105], v[2:17]
	v_exp_f32_e32 v74, v74
	v_exp_f32_e32 v75, v75
	v_exp_f32_e32 v76, v76
	v_exp_f32_e32 v77, v77
	s_waitcnt lgkmcnt(8)
	v_mfma_f32_32x32x16_bf16 v[18:33], v[142:145], v[106:109], v[18:33]
	v_exp_f32_e32 v78, v78
	v_exp_f32_e32 v79, v79
	v_exp_f32_e32 v80, v80
	v_exp_f32_e32 v81, v81
	s_add_u32 s98, s98, 0x2000
	s_addc_u32 s99, s99, 0
	s_add_i32 s6, s31, 0x2000
	s_cmpk_lg_i32 s31, 0x4000
	s_mov_b32 s24, s76
	s_cselect_b32 s76, s6, 0
	s_add_i32 s26, s26, 2
	s_cmp_gt_i32 s26, s91
	s_cbranch_scc1 .Lattn_exit
	s_waitcnt vmcnt(2) lgkmcnt(0)
	s_barrier
.Lattn_cpC:
	ds_read_b64_tr_b16 v[52:53], v200 offset:24576
	ds_read_b64_tr_b16 v[54:55], v200 offset:25088
	v_mfma_f32_32x32x16_bf16 v[114:129], v[190:193], v[150:153], v[34:49]
	s_add_i32 m0, s31, s70
	s_add_i32 s6, s76, s71
	v_add_f32_e32 v50, v82, v50
	v_add_f32_e32 v194, v83, v194
	v_add_f32_e32 v195, v84, v195
	v_add_f32_e32 v196, v85, v196
	v_add_f32_e32 v50, v86, v50
	v_add_f32_e32 v194, v87, v194
	v_cvt_pk_bf16_f32 v158, v82, v83
	v_cvt_pk_bf16_f32 v159, v84, v85
	ds_read_b64_tr_b16 v[60:61], v200 offset:28672
	ds_read_b64_tr_b16 v[62:63], v200 offset:29184
	v_mfma_f32_32x32x16_bf16 v[98:113], v[186:189], v[150:153], v[34:49]
	v_add_f32_e32 v195, v88, v195
	v_add_f32_e32 v196, v89, v196
	v_add_f32_e32 v50, v90, v50
	v_add_f32_e32 v194, v91, v194
	v_cvt_pk_bf16_f32 v160, v86, v87
	v_cvt_pk_bf16_f32 v161, v88, v89
	ds_read_b64_tr_b16 v[82:83], v200 offset:25600
	ds_read_b64_tr_b16 v[84:85], v200 offset:26112
	v_mfma_f32_32x32x16_bf16 v[114:129], v[182:185], v[138:141], v[114:129]
	v_add_f32_e32 v195, v92, v195
	v_add_f32_e32 v196, v93, v196
	v_add_f32_e32 v50, v94, v50
	v_add_f32_e32 v194, v95, v194
	v_cvt_pk_bf16_f32 v154, v90, v91
	v_cvt_pk_bf16_f32 v155, v92, v93
	ds_read_b64_tr_b16 v[86:87], v200 offset:29696
	ds_read_b64_tr_b16 v[88:89], v200 offset:30208
	v_mfma_f32_32x32x16_bf16 v[98:113], v[178:181], v[138:141], v[98:113]
	v_add_f32_e32 v195, v96, v195
	v_add_f32_e32 v196, v97, v196
	v_add_f32_e32 v50, v66, v50
	v_add_f32_e32 v194, v67, v194
	v_cvt_pk_bf16_f32 v156, v94, v95
	v_cvt_pk_bf16_f32 v157, v96, v97
	ds_read_b64_tr_b16 v[90:91], v200 offset:26624
	ds_read_b64_tr_b16 v[92:93], v200 offset:27136
	v_mfma_f32_32x32x16_bf16 v[114:129], v[174:177], v[134:137], v[114:129]
	v_add_f32_e32 v195, v68, v195
	v_add_f32_e32 v196, v69, v196
	v_add_f32_e32 v50, v70, v50
	v_add_f32_e32 v194, v71, v194
	v_cvt_pk_bf16_f32 v146, v66, v67
	v_cvt_pk_bf16_f32 v147, v68, v69
	ds_read_b64_tr_b16 v[64:65], v200 offset:30720
	ds_read_b64_tr_b16 v[66:67], v200 offset:31232
	v_mfma_f32_32x32x16_bf16 v[98:113], v[170:173], v[134:137], v[98:113]
	v_add_f32_e32 v195, v72, v195
	v_add_f32_e32 v196, v73, v196
	v_add_f32_e32 v50, v74, v50
	v_add_f32_e32 v194, v75, v194
	v_cvt_pk_bf16_f32 v148, v70, v71
	v_cvt_pk_bf16_f32 v149, v72, v73
	ds_read_b64_tr_b16 v[68:69], v200 offset:27648
	ds_read_b64_tr_b16 v[70:71], v200 offset:28160
	v_mfma_f32_32x32x16_bf16 v[114:129], v[166:169], v[130:133], v[114:129]
	v_add_f32_e32 v195, v76, v195
	v_add_f32_e32 v196, v77, v196
	v_add_f32_e32 v50, v78, v50
	v_add_f32_e32 v194, v79, v194
	v_cvt_pk_bf16_f32 v142, v74, v75
	v_cvt_pk_bf16_f32 v143, v76, v77
	ds_read_b64_tr_b16 v[72:73], v200 offset:31744
	ds_read_b64_tr_b16 v[74:75], v200 offset:32256
	v_mfma_f32_32x32x16_bf16 v[98:113], v[162:165], v[130:133], v[98:113]
	v_add_f32_e32 v195, v80, v195
	v_add_f32_e32 v196, v81, v196
	v_cvt_pk_bf16_f32 v144, v78, v79
	v_cvt_pk_bf16_f32 v145, v80, v81
	global_load_lds_dwordx4 v197, s[98:99]
	s_mov_b32 m0, s6
	s_nop 0
	global_load_lds_dwordx4 v205, s[98:99]
	s_waitcnt lgkmcnt(14)
	v_mfma_f32_32x32x16_bf16 v[2:17], v[158:161], v[52:55], v[2:17]
	v_exp_f32_e32 v114, v114
	v_exp_f32_e32 v115, v115
	v_exp_f32_e32 v116, v116
	v_exp_f32_e32 v117, v117
	s_waitcnt lgkmcnt(12)
	v_mfma_f32_32x32x16_bf16 v[18:33], v[158:161], v[60:63], v[18:33]
	v_exp_f32_e32 v118, v118
	v_exp_f32_e32 v119, v119
	v_exp_f32_e32 v120, v120
	v_exp_f32_e32 v121, v121
	ds_read_b128 v[60:63], v202
	ds_read_b128 v[162:165], v202 offset:512
	s_waitcnt lgkmcnt(12)
	v_mfma_f32_32x32x16_bf16 v[2:17], v[154:157], v[82:85], v[2:17]
	v_exp_f32_e32 v122, v122
	v_exp_f32_e32 v123, v123
	v_exp_f32_e32 v124, v124
	v_exp_f32_e32 v125, v125
	ds_read_b128 v[166:169], v202 offset:2048
	ds_read_b128 v[170:173], v202 offset:2560
	s_waitcnt lgkmcnt(12)
	v_mfma_f32_32x32x16_bf16 v[18:33], v[154:157], v[86:89], v[18:33]
	v_exp_f32_e32 v126, v126
	v_exp_f32_e32 v127, v127
	v_exp_f32_e32 v128, v128
	v_exp_f32_e32 v129, v129
	ds_read_b128 v[174:177], v202 offset:4096
	ds_read_b128 v[178:181], v202 offset:4608
	s_waitcnt lgkmcnt(12)
	v_mfma_f32_32x32x16_bf16 v[2:17], v[146:149], v[90:93], v[2:17]
	v_exp_f32_e32 v98, v98
	v_exp_f32_e32 v99, v99
	v_exp_f32_e32 v100, v100
	v_exp_f32_e32 v101, v101
	ds_read_b128 v[182:185], v202 offset:6144
	ds_read_b128 v[52:55], v202 offset:6656
	s_waitcnt lgkmcnt(12)
	v_mfma_f32_32x32x16_bf16 v[18:33], v[146:149], v[64:67], v[18:33]
	v_exp_f32_e32 v102, v102
	v_exp_f32_e32 v103, v103
	v_exp_f32_e32 v104, v104
	v_exp_f32_e32 v105, v105
	s_waitcnt lgkmcnt(10)
	v_mfma_f32_32x32x16_bf16 v[2:17], v[142:145], v[68:71], v[2:17]
	v_exp_f32_e32 v106, v106
	v_exp_f32_e32 v107, v107
	v_exp_f32_e32 v108, v108
	v_exp_f32_e32 v109, v109
	s_waitcnt lgkmcnt(8)
	v_mfma_f32_32x32x16_bf16 v[18:33], v[142:145], v[72:75], v[18:33]
	v_exp_f32_e32 v110, v110
	v_exp_f32_e32 v111, v111
	v_exp_f32_e32 v112, v112
	v_exp_f32_e32 v113, v113
	s_add_u32 s98, s98, 0x2000
	s_addc_u32 s99, s99, 0
	s_add_i32 s6, s76, 0x2000
	s_cmpk_lg_i32 s76, 0x4000
	s_cselect_b32 s31, s6, 0
	s_waitcnt vmcnt(2) lgkmcnt(0)
	s_barrier
; #define WAIT_BAR(N) asm volatile("s_waitcnt vmcnt(" #N ") lgkmcnt(0)\n\ts_barrier":::"memory")
;   #define RESC() do{ if(resc){ asm volatile("s_waitcnt lgkmcnt(0)":::"memory"); \
;       _Pragma("unroll") for(int d_=0;d_<2;++d_) _Pragma("unroll") for(int r=0;r<16;++r)o[d_][r]*=wsf[crow(r,hi)]; } }while(0)
;   #define ROT() do{sl_prev=sl_cur;sl_cur=sl_next;sl_next=(sl_next==(NSLOT-1)*SLOTB)?0:sl_next+SLOTB;}while(0)
; template<int THRL> __device__ __forceinline__ void attn_unit(const bf16*Qu,const bf16*__restrict__ Kh,const bf16*__restrict__ Vh,bf16*Ou,const int NT,const float shift,char*shm){
;     ...
;   for(;t+5<NT;t+=2){
;     STEP(pB0,pB1,pA0,pA1,t,true,true,true);     WAIT_BAR(2); RESC(); ROT();
;     STEP(pA0,pA1,pB0,pB1,t+1,true,true,true);   WAIT_BAR(2); RESC(); ROT();
;   }
	ds_read_b64_tr_b16 v[186:187], v201 offset:24576
	ds_read_b64_tr_b16 v[188:189], v201 offset:25088
	v_mfma_f32_32x32x16_bf16 v[82:97], v[60:63], v[150:153], v[34:49]
	s_add_i32 m0, s76, s70
	s_add_i32 s6, s31, s71
	v_add_f32_e32 v50, v114, v50
	v_add_f32_e32 v194, v115, v194
	v_add_f32_e32 v195, v116, v195
	v_add_f32_e32 v196, v117, v196
	v_add_f32_e32 v50, v118, v50
	v_add_f32_e32 v194, v119, v194
	v_cvt_pk_bf16_f32 v158, v114, v115
	v_cvt_pk_bf16_f32 v159, v116, v117
	ds_read_b64_tr_b16 v[60:61], v201 offset:28672
	ds_read_b64_tr_b16 v[62:63], v201 offset:29184
	v_mfma_f32_32x32x16_bf16 v[66:81], v[162:165], v[150:153], v[34:49]
	v_add_f32_e32 v195, v120, v195
	v_add_f32_e32 v196, v121, v196
	v_add_f32_e32 v50, v122, v50
	v_add_f32_e32 v194, v123, v194
	v_cvt_pk_bf16_f32 v160, v118, v119
	v_cvt_pk_bf16_f32 v161, v120, v121
	ds_read_b64_tr_b16 v[114:115], v201 offset:25600
	ds_read_b64_tr_b16 v[116:117], v201 offset:26112
	v_mfma_f32_32x32x16_bf16 v[82:97], v[166:169], v[138:141], v[82:97]
	v_add_f32_e32 v195, v124, v195
	v_add_f32_e32 v196, v125, v196
	v_add_f32_e32 v50, v126, v50
	v_add_f32_e32 v194, v127, v194
	v_cvt_pk_bf16_f32 v154, v122, v123
	v_cvt_pk_bf16_f32 v155, v124, v125
	ds_read_b64_tr_b16 v[118:119], v201 offset:29696
	ds_read_b64_tr_b16 v[120:121], v201 offset:30208
	v_mfma_f32_32x32x16_bf16 v[66:81], v[170:173], v[138:141], v[66:81]
	v_add_f32_e32 v195, v128, v195
	v_add_f32_e32 v196, v129, v196
	v_add_f32_e32 v50, v98, v50
	v_add_f32_e32 v194, v99, v194
	v_cvt_pk_bf16_f32 v156, v126, v127
	v_cvt_pk_bf16_f32 v157, v128, v129
	ds_read_b64_tr_b16 v[122:123], v201 offset:26624
	ds_read_b64_tr_b16 v[124:125], v201 offset:27136
	v_mfma_f32_32x32x16_bf16 v[82:97], v[174:177], v[134:137], v[82:97]
	v_add_f32_e32 v195, v100, v195
	v_add_f32_e32 v196, v101, v196
	v_add_f32_e32 v50, v102, v50
	v_add_f32_e32 v194, v103, v194
	v_cvt_pk_bf16_f32 v146, v98, v99
	v_cvt_pk_bf16_f32 v147, v100, v101
	ds_read_b64_tr_b16 v[98:99], v201 offset:30720
	ds_read_b64_tr_b16 v[100:101], v201 offset:31232
	v_mfma_f32_32x32x16_bf16 v[66:81], v[178:181], v[134:137], v[66:81]
	v_add_f32_e32 v195, v104, v195
	v_add_f32_e32 v196, v105, v196
	v_add_f32_e32 v50, v106, v50
	v_add_f32_e32 v194, v107, v194
	v_cvt_pk_bf16_f32 v148, v102, v103
	v_cvt_pk_bf16_f32 v149, v104, v105
	ds_read_b64_tr_b16 v[102:103], v201 offset:27648
	ds_read_b64_tr_b16 v[104:105], v201 offset:28160
	v_mfma_f32_32x32x16_bf16 v[82:97], v[182:185], v[130:133], v[82:97]
	v_add_f32_e32 v195, v108, v195
	v_add_f32_e32 v196, v109, v196
	v_add_f32_e32 v50, v110, v50
	v_add_f32_e32 v194, v111, v194
	v_cvt_pk_bf16_f32 v142, v106, v107
	v_cvt_pk_bf16_f32 v143, v108, v109
	ds_read_b64_tr_b16 v[106:107], v201 offset:31744
	ds_read_b64_tr_b16 v[108:109], v201 offset:32256
	v_mfma_f32_32x32x16_bf16 v[66:81], v[52:55], v[130:133], v[66:81]
	v_add_f32_e32 v195, v112, v195
	v_add_f32_e32 v196, v113, v196
	v_cvt_pk_bf16_f32 v144, v110, v111
	v_cvt_pk_bf16_f32 v145, v112, v113
	global_load_lds_dwordx4 v197, s[98:99]
	s_mov_b32 m0, s6
	s_nop 0
	global_load_lds_dwordx4 v205, s[98:99]
	s_waitcnt lgkmcnt(14)
	v_mfma_f32_32x32x16_bf16 v[2:17], v[158:161], v[186:189], v[2:17]
	v_exp_f32_e32 v82, v82
	v_exp_f32_e32 v83, v83
	v_exp_f32_e32 v84, v84
	v_exp_f32_e32 v85, v85
	s_waitcnt lgkmcnt(12)
	v_mfma_f32_32x32x16_bf16 v[18:33], v[158:161], v[60:63], v[18:33]
	v_exp_f32_e32 v86, v86
	v_exp_f32_e32 v87, v87
	v_exp_f32_e32 v88, v88
	v_exp_f32_e32 v89, v89
	ds_read_b128 v[190:193], v203
	ds_read_b128 v[186:189], v203 offset:512
	s_waitcnt lgkmcnt(12)
	v_mfma_f32_32x32x16_bf16 v[2:17], v[154:157], v[114:117], v[2:17]
	v_exp_f32_e32 v90, v90
	v_exp_f32_e32 v91, v91
	v_exp_f32_e32 v92, v92
	v_exp_f32_e32 v93, v93
	ds_read_b128 v[182:185], v203 offset:2048
	ds_read_b128 v[178:181], v203 offset:2560
	s_waitcnt lgkmcnt(12)
	v_mfma_f32_32x32x16_bf16 v[18:33], v[154:157], v[118:121], v[18:33]
	v_exp_f32_e32 v94, v94
	v_exp_f32_e32 v95, v95
	v_exp_f32_e32 v96, v96
	v_exp_f32_e32 v97, v97
	ds_read_b128 v[174:177], v203 offset:4096
	ds_read_b128 v[170:173], v203 offset:4608
	s_waitcnt lgkmcnt(12)
	v_mfma_f32_32x32x16_bf16 v[2:17], v[146:149], v[122:125], v[2:17]
	v_exp_f32_e32 v66, v66
	v_exp_f32_e32 v67, v67
	v_exp_f32_e32 v68, v68
	v_exp_f32_e32 v69, v69
	ds_read_b128 v[166:169], v203 offset:6144
	ds_read_b128 v[162:165], v203 offset:6656
	s_waitcnt lgkmcnt(12)
	v_mfma_f32_32x32x16_bf16 v[18:33], v[146:149], v[98:101], v[18:33]
	v_exp_f32_e32 v70, v70
	v_exp_f32_e32 v71, v71
	v_exp_f32_e32 v72, v72
	v_exp_f32_e32 v73, v73
	s_waitcnt lgkmcnt(10)
	v_mfma_f32_32x32x16_bf16 v[2:17], v[142:145], v[102:105], v[2:17]
	v_exp_f32_e32 v74, v74
	v_exp_f32_e32 v75, v75
	v_exp_f32_e32 v76, v76
	v_exp_f32_e32 v77, v77
	s_waitcnt lgkmcnt(8)
	v_mfma_f32_32x32x16_bf16 v[18:33], v[142:145], v[106:109], v[18:33]
	v_exp_f32_e32 v78, v78
	v_exp_f32_e32 v79, v79
	v_exp_f32_e32 v80, v80
	v_exp_f32_e32 v81, v81
	s_add_u32 s98, s98, 0x2000
	s_addc_u32 s99, s99, 0
	s_add_i32 s6, s31, 0x2000
	s_cmpk_lg_i32 s31, 0x4000
	s_mov_b32 s24, s76
	s_cselect_b32 s76, s6, 0
	s_add_i32 s26, s26, 2
	s_cmp_gt_i32 s26, s91
	s_cbranch_scc0 .Lattn_rot
